# in-proj unit order: gate-column tiles (slow two-wave log-sigmoid epilogue) traded from the 89 workgroups with 7 tiles to their +128 partners with 6
# speedup vs baseline: 1.0134x; 1.0059x over previous
;     __host__ __device__ bool next(int i, Unit& u) const { const long L = (long)i * G + c; if (L >= np) return false; u.pm = pm0; u.pn = (int)(L % nN); u.pk = (int)(L / nN); return true; }
;     __host__ __device__ bool next(int i, Unit& u) const {
;         const long L = (long)i * G + c; if (L >= nwg) return false;
;         int wgid = (int)L; { const int q = nwg / NXCD, r = nwg % NXCD, xcd = wgid % NXCD, off = wgid / NXCD; wgid = (xcd < r ? xcd * (q + 1) : r * (q + 1) + (xcd - r) * q) + off; }
;         const int nig = WGM * nN, gid = wgid / nig, fm = gid * WGM, gsz = (nM - fm) < WGM ? (nM - fm) : WGM;
;         u.pm = fm + ((wgid % nig) % gsz); u.pn = (wgid % nig) / gsz; u.pk = 0; return true;
;     }
.LBB0_950:
	s_add_i32 s23, s23, 1
	s_mul_i32 s34, s23, s95
	s_mul_hi_u32 s35, s23, s94
	s_add_i32 s35, s35, s34
	s_mul_i32 s34, s23, s94
	v_readlane_b32 s8, v254, 7
	v_readlane_b32 s9, v254, 8
	s_add_u32 s34, s34, s8
	s_addc_u32 s35, s35, s9
	v_mov_b64_e32 v[2:3], 0x659
	v_cmp_gt_i64_e32 vcc, s[34:35], v[150:151]
	v_cmp_lt_i64_e64 s[40:41], s[34:35], v[2:3]
	s_cbranch_vccnz .LBB0_956
	s_cmp_eq_u32 s94, 0x100
	s_cbranch_scc0 .Lgs_done
	s_cmp_lt_u32 s8, 0x59
	s_cbranch_scc0 .Lgs_notA
	s_and_b32 s74, s34, 7
	s_lshr_b32 s75, s34, 3
	s_mul_i32 s77, s74, 0xcb
	s_cmp_lg_u32 s74, 0
	s_cselect_b32 s74, 1, 0
	s_add_i32 s77, s77, s74
	s_add_i32 s77, s77, s75
	s_mul_hi_u32 s75, s77, 0x51eb851f
	s_lshr_b32 s75, s75, 6
	s_mul_i32 s74, s75, 0xc8
	s_sub_i32 s77, s77, s74
	s_cmp_lt_u32 s75, 8
	s_cselect_b32 s74, 0xc0, 24
	s_cmp_ge_u32 s77, s74
	s_cbranch_scc0 .Lgs_done
	s_cmp_eq_u32 s23, 6
	s_cbranch_scc1 .Lgs_A6
	s_addk_i32 s34, 0x80
	s_branch .Lgs_done
.Lgs_A6:
	s_sub_i32 s79, s34, 0x100
	s_and_b32 s74, s79, 7
	s_lshr_b32 s75, s79, 3
	s_mul_i32 s77, s74, 0xcb
	s_cmp_lg_u32 s74, 0
	s_cselect_b32 s74, 1, 0
	s_add_i32 s77, s77, s74
	s_add_i32 s77, s77, s75
	s_mul_hi_u32 s75, s77, 0x51eb851f
	s_lshr_b32 s75, s75, 6
	s_mul_i32 s74, s75, 0xc8
	s_sub_i32 s77, s77, s74
	s_cmp_lt_u32 s75, 8
	s_cselect_b32 s74, 0xc0, 24
	s_cmp_ge_u32 s77, s74
	s_cbranch_scc1 .Lgs_A6b
	s_sub_i32 s34, s34, 0x80
	s_branch .Lgs_done
.Lgs_A6b:
	s_sub_i32 s34, s34, 0x180
	s_branch .Lgs_done
.Lgs_notA:
	s_sub_i32 s79, s8, 0x80
	s_cmp_lt_u32 s79, 0x59
	s_cbranch_scc0 .Lgs_done
	s_sub_i32 s79, s34, 0x80
	s_and_b32 s74, s79, 7
	s_lshr_b32 s75, s79, 3
	s_mul_i32 s77, s74, 0xcb
	s_cmp_lg_u32 s74, 0
	s_cselect_b32 s74, 1, 0
	s_add_i32 s77, s77, s74
	s_add_i32 s77, s77, s75
	s_mul_hi_u32 s75, s77, 0x51eb851f
	s_lshr_b32 s75, s75, 6
	s_mul_i32 s74, s75, 0xc8
	s_sub_i32 s77, s77, s74
	s_cmp_lt_u32 s75, 8
	s_cselect_b32 s74, 0xc0, 24
	s_cmp_ge_u32 s77, s74
	s_cbranch_scc0 .Lgs_B2
	s_sub_i32 s34, s34, 0x80
	s_branch .Lgs_done
.Lgs_B2:
	s_cmp_eq_u32 s23, 5
	s_cbranch_scc0 .Lgs_B3
	s_add_i32 s79, s34, 0x80
	s_and_b32 s74, s79, 7
	s_lshr_b32 s75, s79, 3
	s_mul_i32 s77, s74, 0xcb
	s_cmp_lg_u32 s74, 0
	s_cselect_b32 s74, 1, 0
	s_add_i32 s77, s77, s74
	s_add_i32 s77, s77, s75
	s_mul_hi_u32 s75, s77, 0x51eb851f
	s_lshr_b32 s75, s75, 6
	s_mul_i32 s74, s75, 0xc8
	s_sub_i32 s77, s77, s74
	s_cmp_lt_u32 s75, 8
	s_cselect_b32 s74, 0xc0, 24
	s_cmp_ge_u32 s77, s74
	s_cbranch_scc0 .Lgs_done
	s_addk_i32 s34, 0x80
	s_branch .Lgs_done
.Lgs_B3:
	s_cmp_eq_u32 s23, 4
	s_cbranch_scc0 .Lgs_done
	s_add_i32 s79, s34, 0x80
	s_and_b32 s74, s79, 7
	s_lshr_b32 s75, s79, 3
	s_mul_i32 s77, s74, 0xcb
	s_cmp_lg_u32 s74, 0
	s_cselect_b32 s74, 1, 0
	s_add_i32 s77, s77, s74
	s_add_i32 s77, s77, s75
	s_mul_hi_u32 s75, s77, 0x51eb851f
	s_lshr_b32 s75, s75, 6
	s_mul_i32 s74, s75, 0xc8
	s_sub_i32 s77, s77, s74
	s_cmp_lt_u32 s75, 8
	s_cselect_b32 s74, 0xc0, 24
	s_cmp_ge_u32 s77, s74
	s_cbranch_scc0 .Lgs_done
	s_add_i32 s79, s34, 0x180
	s_and_b32 s74, s79, 7
	s_lshr_b32 s75, s79, 3
	s_mul_i32 s77, s74, 0xcb
	s_cmp_lg_u32 s74, 0
	s_cselect_b32 s74, 1, 0
	s_add_i32 s77, s77, s74
	s_add_i32 s77, s77, s75
	s_mul_hi_u32 s75, s77, 0x51eb851f
	s_lshr_b32 s75, s75, 6
	s_mul_i32 s74, s75, 0xc8
	s_sub_i32 s77, s77, s74
	s_cmp_lt_u32 s75, 8
	s_cselect_b32 s74, 0xc0, 24
	s_cmp_ge_u32 s77, s74
	s_cbranch_scc0 .Lgs_done
	s_addk_i32 s34, 0x180
.Lgs_done:
	s_ashr_i32 s35, s34, 31
	s_lshr_b32 s35, s35, 29
	s_add_i32 s43, s34, s35
	s_and_b32 s35, s43, -8
	s_sub_i32 s74, s34, s35
	s_cmp_gt_i32 s74, 0
	s_mov_b64 s[34:35], -1
	s_cbranch_scc0 .LBB0_953
	s_mul_i32 s34, s74, 0xcb
	s_add_i32 s75, s34, 1
	s_mov_b64 s[34:35], 0
